# speedup vs baseline: 1.0034x; 1.0034x over previous
; template <int DQK, int MODE> ...
;     ...
;   auto lstore = [&](const TRegs& R, int st) {
;     u16* Ks = lds + st * STG;
;     u16* Vs = Ks + KT;
; #pragma unroll
;     for (int i = 0; i < NKL; ++i) {
;       int c = tid + i * 256;
;       int row = c / KCH, cc = c % KCH;
;       *(u32x4*)(Ks + row * KST + cc * 8) = R.k[i];
;     }
; #pragma unroll
;     for (int i = 0; i < 2; ++i) {
;       int c = tid + i * 256;
;       int d = c >> 3, cc = c & 7;
;       u32x2 lo = {R.v[i].x, R.v[i].y}, hi = {R.v[i].z, R.v[i].w};
;       *(u32x2*)(Vs + d * VST + cc * 8) = lo;
;       *(u32x2*)(Vs + d * VST + cc * 8 + 4) = hi;
;     }
;     ...
;   f32x16 O[2];
; #pragma unroll
;   for (int du = 0; du < 2; ++du)
; #pragma unroll
;     for (int r = 0; r < 16; ++r) O[du][r] = 0.f;
;   float m_run = 0.f, lsum = 0.f;
;   bool first = true;
;   float carry = active ? 1.f : 0.f;
;   const int dir = (MODE == 2) ? -1 : 1;
;   const int jstart = (MODE == 2) ? jhi : jlo;
;   const int ntile = jhi - jlo + 1;
;     ...
;   {
;     TRegs R0, R1;
;     gload(R0, jstart);
;     if (ntile > 1) gload(R1, jstart + dir);
.LBB0_985:
	v_lshlrev_b32_e32 v176, 3, v15
	v_mov_b32_e32 v49, 0
	s_cmp_lt_i32 s4, 0xfff00000
	v_mov_b32_e32 v48, 0
	v_mov_b32_e32 v47, 0
	v_mov_b32_e32 v46, 0
	v_mov_b32_e32 v45, 0
	v_mov_b32_e32 v44, 0
	v_mov_b32_e32 v43, 0
	v_mov_b32_e32 v42, 0
	v_mov_b32_e32 v41, 0
	v_mov_b32_e32 v40, 0
	v_mov_b32_e32 v39, 0
	v_mov_b32_e32 v38, 0
	v_mov_b32_e32 v37, 0
	v_mov_b32_e32 v36, 0
	v_mov_b32_e32 v35, 0
	v_mov_b32_e32 v34, 0
	v_mov_b32_e32 v33, 0
	v_mov_b32_e32 v32, 0
	v_mov_b32_e32 v31, 0
	v_mov_b32_e32 v30, 0
	v_mov_b32_e32 v29, 0
	v_mov_b32_e32 v28, 0
	v_mov_b32_e32 v27, 0
	v_mov_b32_e32 v26, 0
	v_mov_b32_e32 v25, 0
	v_mov_b32_e32 v24, 0
	v_mov_b32_e32 v23, 0
	v_mov_b32_e32 v22, 0
	v_mov_b32_e32 v21, 0
	v_mov_b32_e32 v20, 0
	v_mov_b32_e32 v19, 0
	v_mov_b32_e32 v18, 0
	v_mov_b32_e32 v177, 0
	s_cbranch_scc1 .LBB0_1002
	v_lshl_add_u64 v[178:179], v[4:5], 1, s[16:17]
	v_ashrrev_i32_e32 v5, 7, v14
	v_cndmask_b32_e64 v5, 0, v5, s[0:1]
	v_add_u32_e32 v199, s3, v5
	v_max_i32_e32 v5, 0x100000, v199
	s_movk_i32 s0, 0xd0
	v_add_u32_e32 v200, 0xfff00000, v5
	v_mul_lo_u32 v5, v171, s0
	v_lshl_add_u32 v201, v4, 1, v5
	v_mul_lo_u32 v4, v173, s0
	v_lshl_add_u32 v202, v6, 1, v4
	v_mul_lo_u32 v4, v175, s0
	v_lshl_add_u32 v203, v10, 1, v4
	v_lshrrev_b32_e32 v4, 3, v14
	s_movk_i32 s4, 0x98
	v_mad_u64_u32 v[184:185], s[0:1], v4, s4, v[2:3]
	v_lshrrev_b32_e32 v4, 3, v16
	v_mad_u64_u32 v[186:187], s[0:1], v4, s4, v[2:3]
	v_lshlrev_b32_e32 v2, 1, v176
	v_mul_u32_u24_e32 v4, 0x68, v172
	v_lshl_add_u32 v185, v4, 1, v2
	v_sub_u32_e32 v2, v2, v176
	v_mul_u32_u24_e32 v4, 0x4c, v172
	s_mov_b32 s13, s37
	v_lshl_add_u32 v187, v4, 1, v2
	s_lshl_b64 s[0:1], s[12:13], 13
	v_and_b32_e32 v2, 7, v14
	v_lshl_or_b32 v4, v2, 4, s0
	v_mov_b32_e32 v5, s1
	v_lshl_add_u64 v[180:181], v[6:7], 1, s[16:17]
	v_lshl_add_u64 v[6:7], v[8:9], 1, v[4:5]
	v_lshl_add_u64 v[4:5], v[12:13], 1, v[4:5]
	v_mov_b32_e32 v16, v3
	v_mov_b32_e32 v17, v3
	v_lshl_add_u64 v[182:183], v[10:11], 1, s[16:17]
	v_lshl_add_u64 v[188:189], s[14:15], 0, v[6:7]
	v_lshl_add_u64 v[190:191], s[14:15], 0, v[4:5]
	v_mov_b32_e32 v2, v3
	v_mov_b32_e32 v4, v3
	v_mov_b32_e32 v5, v3
	v_mov_b32_e32 v6, v3
	v_mov_b32_e32 v7, v3
	v_mov_b32_e32 v8, v3
	v_mov_b32_e32 v9, v3
	v_mov_b32_e32 v10, v3
	v_mov_b32_e32 v11, v3
	v_mov_b32_e32 v12, v3
	v_mov_b32_e32 v13, v3
	v_mov_b32_e32 v14, v3
	v_mov_b32_e32 v15, v3
	v_mov_b64_e32 v[32:33], v[16:17]
	v_mov_b64_e32 v[48:49], v[16:17]
	s_mov_b32 s3, 3
	s_lshl_b32 s4, s12, 6
	s_mov_b64 s[0:1], -1
	v_mov_b32_e32 v177, 0
	s_xor_b64 s[14:15], vcc, -1
	v_mov_b64_e32 v[30:31], v[14:15]
	v_mov_b64_e32 v[28:29], v[12:13]
	v_mov_b64_e32 v[26:27], v[10:11]
	v_mov_b64_e32 v[24:25], v[8:9]
	v_mov_b64_e32 v[22:23], v[6:7]
	v_mov_b64_e32 v[20:21], v[4:5]
	v_mov_b64_e32 v[18:19], v[2:3]
	v_mov_b64_e32 v[46:47], v[14:15]
	v_mov_b64_e32 v[44:45], v[12:13]
	v_mov_b64_e32 v[42:43], v[10:11]
	v_mov_b64_e32 v[40:41], v[8:9]
	v_mov_b64_e32 v[38:39], v[6:7]
	v_mov_b64_e32 v[36:37], v[4:5]
	v_mov_b64_e32 v[34:35], v[2:3]
	v_mov_b32_e32 v2, 0
	v_mov_b64_e32 v[228:229], 0
	v_mov_b64_e32 v[230:231], 0
	v_mov_b64_e32 v[232:233], 0
	v_mov_b64_e32 v[234:235], 0
	v_mov_b64_e32 v[236:237], 0
	v_mov_b64_e32 v[238:239], 0
	v_mov_b64_e32 v[240:241], 0
	v_mov_b64_e32 v[242:243], 0
	s_waitcnt vmcnt(0)
	v_add_u32_e32 v226, 0x3400, v184
	ds_write_b128 v201, v[106:109]
	ds_write_b128 v202, v[110:113]
	ds_write_b128 v203, v[114:117]
	ds_write2_b64 v226, v[118:119], v[120:121] offset1:1
	v_add_u32_e32 v226, 0x3400, v186
	ds_write2_b64 v226, v[130:131], v[132:133] offset1:1
	v_add_u32_e32 v220, s4, v171
	v_add_u32_e32 v220, 0xfc000040, v220
	v_add_u32_e32 v222, s4, v173
	v_mad_i64_i32 v[220:221], vcc, v220, s85, v[178:179]
	v_add_u32_e32 v222, 0xfc000040, v222
	v_mad_i64_i32 v[222:223], vcc, v222, s85, v[180:181]
	v_add_u32_e32 v224, s4, v175
	v_add_u32_e32 v224, 0xfc000040, v224
	v_mad_i64_i32 v[224:225], vcc, v224, s85, v[182:183]
	v_lshl_add_u64 v[244:245], v[188:189], 0, s[10:11]
	v_add_co_u32_e32 v244, vcc, 0x2000, v244
	s_nop 1
	v_addc_co_u32_e32 v245, vcc, -2, v245, vcc
	v_lshl_add_u64 v[248:249], v[190:191], 0, s[10:11]
	v_add_co_u32_e32 v248, vcc, 0x2000, v248
	s_nop 1
	v_addc_co_u32_e32 v249, vcc, -2, v249, vcc
	s_nop 0
	v_readfirstlane_b32 s72, v220
	v_readfirstlane_b32 s73, v221
	v_readfirstlane_b32 s74, v244
	v_readfirstlane_b32 s75, v245
	s_lshl_b32 s76, s85, 6
	s_nop 1
	v_subrev_u32_e32 v220, s72, v220
	v_subrev_u32_e32 v222, s72, v222
	v_subrev_u32_e32 v224, s72, v224
	v_subrev_u32_e32 v244, s74, v244
	v_subrev_u32_e32 v248, s74, v248
	s_branch .LBB0_990

; template <int DQK, int MODE> ...
;     ...
;   auto gload = [&](TRegs& R, int j) {
; #pragma unroll
;     for (int i = 0; i < NKL; ++i) {
;       int c = tid + i * 256;
;       int row = c / KCH, cc = c % KCH;
;       R.k[i] = *(const u32x4*)(Kp + (long)(j * 64 + row) * kld + cc * 8);
;     }
; #pragma unroll
;     for (int i = 0; i < 2; ++i) {
;       int c = tid + i * 256;
;       int d = c >> 3, cc = c & 7;
;       R.v[i] = *(const u32x4*)(VTp + (long)j * 4096 + d * 64 + cc * 8);
;     }
;   };
;     ...
;   auto step = [&](TRegs& R, int it) -> bool {
;     const int j = jstart + dir * it;
;     const int st = it & 1;
;     lstore(R, st);
;     if (MODE == 2) {
;       int alive = (carry != 0.f) ? 1 : 0;
;       if (!__syncthreads_or(alive)) return false;
;     } else {
;       __syncthreads();
;     }
;     if (it + 2 < ntile) gload(R, j + 2 * dir);
.LBB0_990:
	s_add_u32 s72, s72, s76
	s_addc_u32 s73, s73, 0
	s_add_u32 s74, s74, 0x2000
	s_addc_u32 s75, s75, 0
	s_add_i32 s6, s12, s3
	s_add_i32 s7, s6, 0xffeffffd
	v_cmp_le_i32_e32 vcc, s7, v199
	s_and_b64 s[16:17], s[14:15], vcc
	v_cmp_ge_u32_e32 vcc, s7, v200
	s_and_b64 s[18:19], s[16:17], vcc
	s_add_i32 s5, s3, -1
	s_cmp_gt_i32 s5, s2
	s_waitcnt lgkmcnt(0)
	s_barrier
	s_cbranch_scc1 .LBB0_992
	global_load_dwordx4 v[106:109], v220, s[72:73]
	global_load_dwordx4 v[110:113], v222, s[72:73]
	global_load_dwordx4 v[114:117], v224, s[72:73]
	global_load_dwordx4 v[118:121], v244, s[74:75]
	global_load_dwordx4 v[130:133], v248, s[74:75]

; template <int DQK, int MODE> ...
;     ...
;   auto gload = [&](TRegs& R, int j) {
; #pragma unroll
;     for (int i = 0; i < NKL; ++i) {
;       int c = tid + i * 256;
;       int row = c / KCH, cc = c % KCH;
;       R.k[i] = *(const u32x4*)(Kp + (long)(j * 64 + row) * kld + cc * 8);
;     }
; #pragma unroll
;     for (int i = 0; i < 2; ++i) {
;       int c = tid + i * 256;
;       int d = c >> 3, cc = c & 7;
;       R.v[i] = *(const u32x4*)(VTp + (long)j * 4096 + d * 64 + cc * 8);
;     }
;   };
;     ...
;   auto step = [&](TRegs& R, int it) -> bool {
;     const int j = jstart + dir * it;
;     const int st = it & 1;
;     lstore(R, st);
;     if (MODE == 2) {
;       int alive = (carry != 0.f) ? 1 : 0;
;       if (!__syncthreads_or(alive)) return false;
;     } else {
;       __syncthreads();
;     }
;     if (it + 2 < ntile) gload(R, j + 2 * dir);
.Lmy_w3_dn:
.LBB0_996:
	s_or_b64 exec, exec, s[16:17]
	s_add_i32 s7, s3, -3
	s_cmp_ge_i32 s7, s2
	s_cbranch_scc1 .LBB0_989
	s_add_u32 s72, s72, s76
	s_addc_u32 s73, s73, 0
	s_add_u32 s74, s74, 0x2000
	s_addc_u32 s75, s75, 0
	s_add_i32 s13, s6, 0xffeffffe
	v_cmp_le_i32_e32 vcc, s13, v199
	s_and_b64 s[6:7], s[14:15], vcc
	v_cmp_ge_u32_e32 vcc, s13, v200
	s_and_b64 s[6:7], s[6:7], vcc
	s_cmp_gt_i32 s3, s2
	s_waitcnt lgkmcnt(0)
	s_barrier
	s_cbranch_scc1 .LBB0_999
	global_load_dwordx4 v[122:125], v220, s[72:73]
	global_load_dwordx4 v[126:129], v222, s[72:73]
	global_load_dwordx4 v[134:137], v224, s[72:73]
	global_load_dwordx4 v[138:141], v244, s[74:75]
	global_load_dwordx4 v[142:145], v248, s[74:75]

; template <int DQK, int MODE> ...
;     ...
;   auto lstore = [&](const TRegs& R, int st) {
;     u16* Ks = lds + st * STG;
;     u16* Vs = Ks + KT;
; #pragma unroll
;     for (int i = 0; i < NKL; ++i) {
;       int c = tid + i * 256;
;       int row = c / KCH, cc = c % KCH;
;       *(u32x4*)(Ks + row * KST + cc * 8) = R.k[i];
;     }
; #pragma unroll
;     for (int i = 0; i < 2; ++i) {
;       int c = tid + i * 256;
;       int d = c >> 3, cc = c & 7;
;       u32x2 lo = {R.v[i].x, R.v[i].y}, hi = {R.v[i].z, R.v[i].w};
;       *(u32x2*)(Vs + d * VST + cc * 8) = lo;
;       *(u32x2*)(Vs + d * VST + cc * 8 + 4) = hi;
;     }
;     ...
;   f32x16 O[2];
; #pragma unroll
;   for (int du = 0; du < 2; ++du)
; #pragma unroll
;     for (int r = 0; r < 16; ++r) O[du][r] = 0.f;
;   float m_run = 0.f, lsum = 0.f;
;   bool first = true;
;   float carry = active ? 1.f : 0.f;
;   const int dir = (MODE == 2) ? -1 : 1;
;   const int jstart = (MODE == 2) ? jhi : jlo;
;   const int ntile = jhi - jlo + 1;
;     ...
;   {
;     TRegs R0, R1;
;     gload(R0, jstart);
;     if (ntile > 1) gload(R1, jstart + dir);
.LBB0_2122:
	v_lshlrev_b32_e32 v174, 3, v13
	v_mov_b32_e32 v47, 0
	s_cmp_lt_i32 s9, 0xfff00000
	v_mov_b32_e32 v46, 0
	v_mov_b32_e32 v45, 0
	v_mov_b32_e32 v44, 0
	v_mov_b32_e32 v43, 0
	v_mov_b32_e32 v42, 0
	v_mov_b32_e32 v41, 0
	v_mov_b32_e32 v40, 0
	v_mov_b32_e32 v39, 0
	v_mov_b32_e32 v38, 0
	v_mov_b32_e32 v37, 0
	v_mov_b32_e32 v36, 0
	v_mov_b32_e32 v35, 0
	v_mov_b32_e32 v34, 0
	v_mov_b32_e32 v33, 0
	v_mov_b32_e32 v32, 0
	v_mov_b32_e32 v31, 0
	v_mov_b32_e32 v30, 0
	v_mov_b32_e32 v29, 0
	v_mov_b32_e32 v28, 0
	v_mov_b32_e32 v27, 0
	v_mov_b32_e32 v26, 0
	v_mov_b32_e32 v25, 0
	v_mov_b32_e32 v24, 0
	v_mov_b32_e32 v23, 0
	v_mov_b32_e32 v22, 0
	v_mov_b32_e32 v21, 0
	v_mov_b32_e32 v20, 0
	v_mov_b32_e32 v19, 0
	v_mov_b32_e32 v18, 0
	v_mov_b32_e32 v17, 0
	v_mov_b32_e32 v16, 0
	v_mov_b32_e32 v175, 0
	s_cbranch_scc1 .LBB0_2139
	v_lshl_add_u64 v[176:177], v[2:3], 1, s[12:13]
	v_ashrrev_i32_e32 v3, 7, v12
	v_cndmask_b32_e64 v3, 0, v3, s[46:47]
	v_add_u32_e32 v197, s14, v3
	v_max_i32_e32 v3, 0x100000, v197
	s_movk_i32 s9, 0xd0
	v_add_u32_e32 v199, 0xfff00000, v3
	v_mul_lo_u32 v3, v169, s9
	v_lshl_add_u32 v200, v2, 1, v3
	v_mul_lo_u32 v2, v171, s9
	v_lshl_add_u32 v201, v4, 1, v2
	v_mul_lo_u32 v2, v173, s9
	v_lshl_add_u32 v202, v8, 1, v2
	v_lshrrev_b32_e32 v2, 3, v12
	v_lshl_add_u64 v[178:179], v[4:5], 1, s[12:13]
	v_lshl_add_u64 v[180:181], v[8:9], 1, s[12:13]
	v_mad_u64_u32 v[182:183], s[12:13], v2, s95, v[0:1]
	v_lshrrev_b32_e32 v2, 3, v14
	v_mad_u64_u32 v[184:185], s[12:13], v2, s95, v[0:1]
	v_lshlrev_b32_e32 v0, 1, v174
	v_mul_u32_u24_e32 v2, 0x68, v170
	v_lshl_add_u32 v183, v2, 1, v0
	v_sub_u32_e32 v0, v0, v174
	v_mul_u32_u24_e32 v2, 0x4c, v170
	s_mov_b32 s9, s19
	v_lshl_add_u32 v185, v2, 1, v0
	s_lshl_b64 s[12:13], s[8:9], 13
	v_and_b32_e32 v0, 7, v12
	v_lshl_or_b32 v2, v0, 4, s12
	v_mov_b32_e32 v3, s13
	v_lshl_add_u64 v[4:5], v[6:7], 1, v[2:3]
	v_lshl_add_u64 v[2:3], v[10:11], 1, v[2:3]
	v_mov_b32_e32 v14, v1
	v_mov_b32_e32 v15, v1
	v_lshl_add_u64 v[186:187], s[10:11], 0, v[4:5]
	v_lshl_add_u64 v[188:189], s[10:11], 0, v[2:3]
	v_mov_b32_e32 v0, v1
	v_mov_b32_e32 v2, v1
	v_mov_b32_e32 v3, v1
	v_mov_b32_e32 v4, v1
	v_mov_b32_e32 v5, v1
	v_mov_b32_e32 v6, v1
	v_mov_b32_e32 v7, v1
	v_mov_b32_e32 v8, v1
	v_mov_b32_e32 v9, v1
	v_mov_b32_e32 v10, v1
	v_mov_b32_e32 v11, v1
	v_mov_b32_e32 v12, v1
	v_mov_b32_e32 v13, v1
	v_mov_b64_e32 v[30:31], v[14:15]
	v_mov_b64_e32 v[46:47], v[14:15]
	s_mov_b32 s17, 3
	s_lshl_b32 s9, s8, 6
	s_mov_b64 s[10:11], -1
	v_mov_b32_e32 v175, 0
	s_xor_b64 s[12:13], vcc, -1
	v_mov_b64_e32 v[28:29], v[12:13]
	v_mov_b64_e32 v[26:27], v[10:11]
	v_mov_b64_e32 v[24:25], v[8:9]
	v_mov_b64_e32 v[22:23], v[6:7]
	v_mov_b64_e32 v[20:21], v[4:5]
	v_mov_b64_e32 v[18:19], v[2:3]
	v_mov_b64_e32 v[16:17], v[0:1]
	v_mov_b64_e32 v[44:45], v[12:13]
	v_mov_b64_e32 v[42:43], v[10:11]
	v_mov_b64_e32 v[40:41], v[8:9]
	v_mov_b64_e32 v[38:39], v[6:7]
	v_mov_b64_e32 v[36:37], v[4:5]
	v_mov_b64_e32 v[34:35], v[2:3]
	v_mov_b64_e32 v[32:33], v[0:1]
	v_mov_b32_e32 v0, 0
	v_mov_b64_e32 v[228:229], 0
	v_mov_b64_e32 v[230:231], 0
	v_mov_b64_e32 v[232:233], 0
	v_mov_b64_e32 v[234:235], 0
	v_mov_b64_e32 v[236:237], 0
	v_mov_b64_e32 v[238:239], 0
	v_mov_b64_e32 v[240:241], 0
	v_mov_b64_e32 v[242:243], 0
	s_waitcnt vmcnt(0)
	v_add_u32_e32 v226, 0x3400, v182
	ds_write_b128 v200, v[104:107]
	ds_write_b128 v201, v[108:111]
	ds_write_b128 v202, v[112:115]
	ds_write2_b64 v226, v[116:117], v[118:119] offset1:1
	v_add_u32_e32 v226, 0x3400, v184
	ds_write2_b64 v226, v[128:129], v[130:131] offset1:1
	v_add_u32_e32 v220, s9, v169
	v_add_u32_e32 v220, 0xfc000040, v220
	v_add_u32_e32 v222, s9, v171
	v_mad_i64_i32 v[220:221], vcc, v220, s87, v[176:177]
	v_add_u32_e32 v222, 0xfc000040, v222
	v_mad_i64_i32 v[222:223], vcc, v222, s87, v[178:179]
	v_add_u32_e32 v224, s9, v173
	v_add_u32_e32 v224, 0xfc000040, v224
	v_mad_i64_i32 v[224:225], vcc, v224, s87, v[180:181]
	v_lshl_add_u64 v[244:245], v[186:187], 0, s[2:3]
	v_add_co_u32_e32 v244, vcc, 0x2000, v244
	s_nop 1
	v_addc_co_u32_e32 v245, vcc, -2, v245, vcc
	v_lshl_add_u64 v[248:249], v[188:189], 0, s[2:3]
	v_add_co_u32_e32 v248, vcc, 0x2000, v248
	s_nop 1
	v_addc_co_u32_e32 v249, vcc, -2, v249, vcc
	s_nop 0
	v_readfirstlane_b32 s72, v220
	v_readfirstlane_b32 s73, v221
	v_readfirstlane_b32 s74, v244
	v_readfirstlane_b32 s75, v245
	s_lshl_b32 s76, s87, 6
	s_nop 1
	v_subrev_u32_e32 v220, s72, v220
	v_subrev_u32_e32 v222, s72, v222
	v_subrev_u32_e32 v224, s72, v224
	v_subrev_u32_e32 v244, s74, v244
	v_subrev_u32_e32 v248, s74, v248
	s_branch .LBB0_2127

; template <int DQK, int MODE> ...
;     ...
;   auto gload = [&](TRegs& R, int j) {
; #pragma unroll
;     for (int i = 0; i < NKL; ++i) {
;       int c = tid + i * 256;
;       int row = c / KCH, cc = c % KCH;
;       R.k[i] = *(const u32x4*)(Kp + (long)(j * 64 + row) * kld + cc * 8);
;     }
; #pragma unroll
;     for (int i = 0; i < 2; ++i) {
;       int c = tid + i * 256;
;       int d = c >> 3, cc = c & 7;
;       R.v[i] = *(const u32x4*)(VTp + (long)j * 4096 + d * 64 + cc * 8);
;     }
;   };
;     ...
;   auto step = [&](TRegs& R, int it) -> bool {
;     const int j = jstart + dir * it;
;     const int st = it & 1;
;     lstore(R, st);
;     if (MODE == 2) {
;       int alive = (carry != 0.f) ? 1 : 0;
;       if (!__syncthreads_or(alive)) return false;
;     } else {
;       __syncthreads();
;     }
;     if (it + 2 < ntile) gload(R, j + 2 * dir);
.LBB0_2127:
	s_add_u32 s72, s72, s76
	s_addc_u32 s73, s73, 0
	s_add_u32 s74, s74, 0x2000
	s_addc_u32 s75, s75, 0
	s_add_i32 s21, s8, s17
	s_add_i32 s30, s21, 0xffeffffd
	v_cmp_le_i32_e32 vcc, s30, v197
	s_and_b64 s[14:15], s[12:13], vcc
	v_cmp_ge_u32_e32 vcc, s30, v199
	s_and_b64 s[30:31], s[14:15], vcc
	s_add_i32 s18, s17, -1
	s_cmp_gt_i32 s18, s16
	s_waitcnt lgkmcnt(0)
	s_barrier
	s_cbranch_scc1 .LBB0_2129
	global_load_dwordx4 v[104:107], v220, s[72:73]
	global_load_dwordx4 v[108:111], v222, s[72:73]
	global_load_dwordx4 v[112:115], v224, s[72:73]
	global_load_dwordx4 v[116:119], v244, s[74:75]
	global_load_dwordx4 v[128:131], v248, s[74:75]

; template <int DQK, int MODE> ...
;     ...
;   auto gload = [&](TRegs& R, int j) {
; #pragma unroll
;     for (int i = 0; i < NKL; ++i) {
;       int c = tid + i * 256;
;       int row = c / KCH, cc = c % KCH;
;       R.k[i] = *(const u32x4*)(Kp + (long)(j * 64 + row) * kld + cc * 8);
;     }
; #pragma unroll
;     for (int i = 0; i < 2; ++i) {
;       int c = tid + i * 256;
;       int d = c >> 3, cc = c & 7;
;       R.v[i] = *(const u32x4*)(VTp + (long)j * 4096 + d * 64 + cc * 8);
;     }
;   };
;     ...
;   auto step = [&](TRegs& R, int it) -> bool {
;     const int j = jstart + dir * it;
;     const int st = it & 1;
;     lstore(R, st);
;     if (MODE == 2) {
;       int alive = (carry != 0.f) ? 1 : 0;
;       if (!__syncthreads_or(alive)) return false;
;     } else {
;       __syncthreads();
;     }
;     if (it + 2 < ntile) gload(R, j + 2 * dir);
.Lmy_w7_dn:
.LBB0_2133:
	s_or_b64 exec, exec, s[14:15]
	s_add_i32 s14, s17, -3
	s_cmp_ge_i32 s14, s16
	s_cbranch_scc1 .LBB0_2126
	s_add_u32 s72, s72, s76
	s_addc_u32 s73, s73, 0
	s_add_u32 s74, s74, 0x2000
	s_addc_u32 s75, s75, 0
	s_add_i32 s21, s21, 0xffeffffe
	v_cmp_le_i32_e32 vcc, s21, v197
	s_and_b64 s[14:15], s[12:13], vcc
	v_cmp_ge_u32_e32 vcc, s21, v199
	s_and_b64 s[30:31], s[14:15], vcc
	s_cmp_gt_i32 s17, s16
	s_waitcnt lgkmcnt(0)
	s_barrier
	s_cbranch_scc1 .LBB0_2136
	global_load_dwordx4 v[120:123], v220, s[72:73]
	global_load_dwordx4 v[124:127], v222, s[72:73]
	global_load_dwordx4 v[132:135], v224, s[72:73]
	global_load_dwordx4 v[136:139], v244, s[74:75]
	global_load_dwordx4 v[140:143], v248, s[74:75]
